# indexer pass 1 touches pass 2's query rows so pass 2's requests hit L2
# baseline (speedup 1.0000x reference)
; #define GAS __attribute__((address_space(1)))
; __device__ __forceinline__ void indexer_unit(const Args& a, LAS unsigned char* lds, LAS unsigned long long* maskl, int b, int qblk, int wave, int lane) {
;     ...
;     const int fr = lane & 15, fq = lane >> 4, t0 = qblk * 16; const size_t rowb = (size_t)b * SEQ;
;     bf16x8 af[8][2]; float wv[8][4];
; #pragma unroll
;     for (int rt = 0; rt < 8; ++rt) {
;         const GAS bf16* p = z + (rowb + t0 + 2 * rt + (fr >> 3)) * ZW + ZIQ + (fr & 7) * 64 + 8 * fq;
;         af[rt][0] = __builtin_nontemporal_load((const GAS bf16x8*)p); af[rt][1] = __builtin_nontemporal_load((const GAS bf16x8*)(p + 32));
;         const u32x2 w = *(const GAS u32x2*)(z + (rowb + t0 + 2 * rt + (fq >> 1)) * ZW + ZIW + 4 * (fq & 1));
;         wv[rt][0] = bflo(w.x); wv[rt][1] = bfhi(w.x); wv[rt][2] = bflo(w.y); wv[rt][3] = bfhi(w.y);
;     }
.LBB0_1082:
	v_readlane_b32 s2, v254, 44
	v_mov_b32_e32 v76, v252
	s_or_b32 s9, s8, s2
	s_lshl_b32 s76, s9, 4
	v_and_b32_e32 v5, 63, v76
	v_readlane_b32 s2, v254, 4
	s_cmp_gt_u32 s2, s9
	v_lshlrev_b32_e32 v84, 6, v5
	s_cbranch_scc1 .LBB0_1101
	s_cmp_eq_u32 s8, 0
	s_cselect_b32 s16, 0x1e000, 0
	s_mov_b32 s17, 0
	v_readlane_b32 s14, v254, 46
	v_readlane_b32 s4, v254, 24
	s_add_i32 s2, s76, s14
	v_bfe_u32 v57, v76, 3, 1
	v_readlane_b32 s5, v254, 25
	v_and_b32_e32 v2, 0x1c0, v84
	v_or_b32_e32 v0, s2, v57
	v_mov_b64_e32 v[46:47], s[4:5]
	s_movk_i32 s10, 0x1e00
	v_mad_u64_u32 v[0:1], s[4:5], v0, s10, v[46:47]
	v_lshlrev_b32_e32 v48, 1, v2
	v_mov_b32_e32 v49, v4
	v_lshrrev_b32_e32 v119, 5, v5
	v_lshl_add_u64 v[0:1], v[0:1], 0, v[48:49]
	v_and_b32_e32 v74, 48, v5
	v_mov_b32_e32 v75, v4
	v_lshl_add_u64 v[0:1], v[0:1], 0, v[74:75]
	s_mov_b64 s[12:13], 0x1900
	v_or_b32_e32 v10, s2, v119
	v_lshrrev_b32_e32 v12, 1, v5
	s_or_b32 s3, s2, 2
	v_lshl_add_u64 v[6:7], v[0:1], 0, s[12:13]
	v_add_co_u32_e32 v0, vcc, 0x1000, v0
	v_mad_u64_u32 v[10:11], s[4:5], v10, s10, v[46:47]
	v_and_b32_e32 v50, 8, v12
	v_mov_b32_e32 v51, v4
	v_or_b32_e32 v12, s3, v57
	v_addc_co_u32_e32 v1, vcc, 0, v1, vcc
	v_lshl_add_u64 v[10:11], v[10:11], 0, v[50:51]
	v_mad_u64_u32 v[12:13], s[4:5], v12, s10, v[46:47]
	v_add_co_u32_e32 v10, vcc, 0x1000, v10
	v_lshl_add_u64 v[12:13], v[12:13], 0, v[48:49]
	s_nop 0
	v_addc_co_u32_e32 v11, vcc, 0, v11, vcc
	v_lshl_add_u64 v[12:13], v[12:13], 0, v[74:75]
	s_movk_i32 s11, 0x1000
	v_lshl_add_u64 v[14:15], v[12:13], 0, s[12:13]
	v_add_co_u32_e32 v16, vcc, s11, v12
	v_lshl_add_u64 v[126:127], v[0:1], 0, s[16:17]
	global_load_dword v125, v[126:127], off offset:2304
	global_load_dwordx4 v[0:3], v[0:1], off offset:2304 nt
	s_nop 0
	v_lshl_add_u64 v[126:127], v[6:7], 0, s[16:17]
	global_load_dword v125, v[126:127], off offset:64
	global_load_dwordx4 v[6:9], v[6:7], off offset:64 nt
	v_addc_co_u32_e32 v17, vcc, 0, v13, vcc
	v_lshl_add_u64 v[126:127], v[10:11], 0, s[16:17]
	global_load_dword v125, v[126:127], off offset:3472
	global_load_dwordx2 v[78:79], v[10:11], off offset:3472
	s_nop 0
	v_lshl_add_u64 v[126:127], v[14:15], 0, s[16:17]
	global_load_dword v125, v[126:127], off offset:64
	global_load_dwordx4 v[10:13], v[14:15], off offset:64 nt
	v_or_b32_e32 v14, s3, v119
	v_mad_u64_u32 v[14:15], s[4:5], v14, s10, v[46:47]
	v_lshl_add_u64 v[14:15], v[14:15], 0, v[50:51]
	v_add_co_u32_e32 v18, vcc, s11, v14
	s_or_b32 s3, s2, 4
	s_nop 0
	v_addc_co_u32_e32 v19, vcc, 0, v15, vcc
	v_lshl_add_u64 v[126:127], v[16:17], 0, s[16:17]
	global_load_dword v125, v[126:127], off offset:2304
	global_load_dwordx4 v[14:17], v[16:17], off offset:2304 nt
	s_nop 0
	v_lshl_add_u64 v[126:127], v[18:19], 0, s[16:17]
	global_load_dword v125, v[126:127], off offset:3472
	global_load_dwordx2 v[80:81], v[18:19], off offset:3472
	v_or_b32_e32 v18, s3, v57
	v_mad_u64_u32 v[18:19], s[4:5], v18, s10, v[46:47]
	v_lshl_add_u64 v[18:19], v[18:19], 0, v[48:49]
	v_lshl_add_u64 v[18:19], v[18:19], 0, v[74:75]
	v_or_b32_e32 v26, s3, v119
	s_or_b32 s3, s2, 6
	v_lshl_add_u64 v[22:23], v[18:19], 0, s[12:13]
	v_add_co_u32_e32 v18, vcc, s11, v18
	v_mad_u64_u32 v[26:27], s[4:5], v26, s10, v[46:47]
	v_or_b32_e32 v28, s3, v57
	v_addc_co_u32_e32 v19, vcc, 0, v19, vcc
	v_lshl_add_u64 v[26:27], v[26:27], 0, v[50:51]
	v_mad_u64_u32 v[28:29], s[4:5], v28, s10, v[46:47]
	v_add_co_u32_e32 v26, vcc, s11, v26
	v_lshl_add_u64 v[28:29], v[28:29], 0, v[48:49]
	s_nop 0
	v_addc_co_u32_e32 v27, vcc, 0, v27, vcc
	v_lshl_add_u64 v[28:29], v[28:29], 0, v[74:75]
	v_lshl_add_u64 v[30:31], v[28:29], 0, s[12:13]
	v_add_co_u32_e32 v32, vcc, s11, v28
	v_lshl_add_u64 v[126:127], v[18:19], 0, s[16:17]
	global_load_dword v125, v[126:127], off offset:2304
	global_load_dwordx4 v[18:21], v[18:19], off offset:2304 nt
	s_nop 0
	v_lshl_add_u64 v[126:127], v[22:23], 0, s[16:17]
	global_load_dword v125, v[126:127], off offset:64
	global_load_dwordx4 v[22:25], v[22:23], off offset:64 nt
	v_addc_co_u32_e32 v33, vcc, 0, v29, vcc
	v_lshl_add_u64 v[126:127], v[26:27], 0, s[16:17]
	global_load_dword v125, v[126:127], off offset:3472
	global_load_dwordx2 v[82:83], v[26:27], off offset:3472
	s_nop 0
	v_lshl_add_u64 v[126:127], v[30:31], 0, s[16:17]
	global_load_dword v125, v[126:127], off offset:64
	global_load_dwordx4 v[26:29], v[30:31], off offset:64 nt
	v_or_b32_e32 v30, s3, v119
	v_mad_u64_u32 v[30:31], s[4:5], v30, s10, v[46:47]
	v_lshl_add_u64 v[30:31], v[30:31], 0, v[50:51]
	v_add_co_u32_e32 v34, vcc, s11, v30
	s_or_b32 s3, s2, 8
	s_nop 0
	v_addc_co_u32_e32 v35, vcc, 0, v31, vcc
	v_lshl_add_u64 v[126:127], v[32:33], 0, s[16:17]
	global_load_dword v125, v[126:127], off offset:2304
	global_load_dwordx4 v[30:33], v[32:33], off offset:2304 nt
	s_nop 0
	v_lshl_add_u64 v[126:127], v[34:35], 0, s[16:17]
	global_load_dword v125, v[126:127], off offset:3472
	global_load_dwordx2 v[100:101], v[34:35], off offset:3472
	v_or_b32_e32 v34, s3, v57
	v_mad_u64_u32 v[34:35], s[4:5], v34, s10, v[46:47]
	v_lshl_add_u64 v[34:35], v[34:35], 0, v[48:49]
	v_lshl_add_u64 v[34:35], v[34:35], 0, v[74:75]
	v_or_b32_e32 v42, s3, v119
	v_lshl_add_u64 v[38:39], v[34:35], 0, s[12:13]
	v_add_co_u32_e32 v34, vcc, s11, v34
	v_mad_u64_u32 v[42:43], s[4:5], v42, s10, v[46:47]
	s_nop 0
	v_addc_co_u32_e32 v35, vcc, 0, v35, vcc
	v_lshl_add_u64 v[42:43], v[42:43], 0, v[50:51]
	v_add_co_u32_e32 v42, vcc, s11, v42
	s_or_b32 s3, s2, 10
	s_nop 0
	v_addc_co_u32_e32 v43, vcc, 0, v43, vcc
	v_lshl_add_u64 v[126:127], v[34:35], 0, s[16:17]
; #define GAS __attribute__((address_space(1)))
; __device__ __forceinline__ void indexer_unit(const Args& a, LAS unsigned char* lds, LAS unsigned long long* maskl, int b, int qblk, int wave, int lane) {
;     ...
;     const int fr = lane & 15, fq = lane >> 4, t0 = qblk * 16; const size_t rowb = (size_t)b * SEQ;
;     bf16x8 af[8][2]; float wv[8][4];
; #pragma unroll
;     for (int rt = 0; rt < 8; ++rt) {
;         const GAS bf16* p = z + (rowb + t0 + 2 * rt + (fr >> 3)) * ZW + ZIQ + (fr & 7) * 64 + 8 * fq;
;         af[rt][0] = __builtin_nontemporal_load((const GAS bf16x8*)p); af[rt][1] = __builtin_nontemporal_load((const GAS bf16x8*)(p + 32));
;         const u32x2 w = *(const GAS u32x2*)(z + (rowb + t0 + 2 * rt + (fq >> 1)) * ZW + ZIW + 4 * (fq & 1));
;         wv[rt][0] = bflo(w.x); wv[rt][1] = bfhi(w.x); wv[rt][2] = bflo(w.y); wv[rt][3] = bfhi(w.y);
;     }
;     const int nkt = qblk + 1;
;     bf16x8 nb0, nb1;
;     { const int k0 = wave < nkt ? wave : 0; const GAS bf16* p = ikn + (rowb + 16 * k0 + fr) * 64 + 8 * fq; nb0 = *(const GAS bf16x8*)p; nb1 = *(const GAS bf16x8*)(p + 32); }
	global_load_dword v125, v[126:127], off offset:2304
	global_load_dwordx4 v[34:37], v[34:35], off offset:2304 nt
	s_nop 0
	v_lshl_add_u64 v[126:127], v[38:39], 0, s[16:17]
	global_load_dword v125, v[126:127], off offset:64
	global_load_dwordx4 v[38:41], v[38:39], off offset:64 nt
	v_or_b32_e32 v44, s3, v119
	v_lshl_add_u64 v[126:127], v[42:43], 0, s[16:17]
	global_load_dword v125, v[126:127], off offset:3472
	global_load_dwordx2 v[104:105], v[42:43], off offset:3472
	v_or_b32_e32 v42, s3, v57
	v_mad_u64_u32 v[42:43], s[4:5], v42, s10, v[46:47]
	v_lshl_add_u64 v[42:43], v[42:43], 0, v[48:49]
	v_lshl_add_u64 v[42:43], v[42:43], 0, v[74:75]
	v_lshl_add_u64 v[52:53], v[42:43], 0, s[12:13]
	v_add_co_u32_e32 v42, vcc, s11, v42
	v_mad_u64_u32 v[44:45], s[4:5], v44, s10, v[46:47]
	s_nop 0
	v_addc_co_u32_e32 v43, vcc, 0, v43, vcc
	v_lshl_add_u64 v[44:45], v[44:45], 0, v[50:51]
	v_add_co_u32_e32 v54, vcc, s11, v44
	s_or_b32 s3, s2, 12
	s_nop 0
	v_addc_co_u32_e32 v55, vcc, 0, v45, vcc
	v_lshl_add_u64 v[126:127], v[42:43], 0, s[16:17]
	global_load_dword v125, v[126:127], off offset:2304
	global_load_dwordx4 v[42:45], v[42:43], off offset:2304 nt
	s_nop 0
	v_lshl_add_u64 v[126:127], v[54:55], 0, s[16:17]
	global_load_dword v125, v[126:127], off offset:3472
	global_load_dwordx2 v[108:109], v[54:55], off offset:3472
	v_or_b32_e32 v54, s3, v57
	v_mad_u64_u32 v[54:55], s[4:5], v54, s10, v[46:47]
	v_lshl_add_u64 v[54:55], v[54:55], 0, v[48:49]
	v_or_b32_e32 v58, s3, v119
	v_lshl_add_u64 v[54:55], v[54:55], 0, v[74:75]
	v_mad_u64_u32 v[58:59], s[4:5], v58, s10, v[46:47]
	v_add_co_u32_e32 v56, vcc, s11, v54
	v_lshl_add_u64 v[58:59], v[58:59], 0, v[50:51]
	s_mov_b64 s[6:7], vcc
	v_add_co_u32_e32 v58, vcc, s11, v58
	s_or_b32 s4, s2, 14
	s_nop 0
	v_addc_co_u32_e32 v59, vcc, 0, v59, vcc
	v_or_b32_e32 v57, s4, v57
	v_lshl_add_u64 v[126:127], v[58:59], 0, s[16:17]
	global_load_dword v125, v[126:127], off offset:3472
	global_load_dwordx2 v[112:113], v[58:59], off offset:3472
	v_mad_u64_u32 v[58:59], s[2:3], v57, s10, v[46:47]
	v_or_b32_e32 v57, s4, v119
	v_lshl_add_u64 v[48:49], v[58:59], 0, v[48:49]
	v_mad_u64_u32 v[46:47], s[2:3], v57, s10, v[46:47]
	v_and_b32_e32 v77, 15, v76
	v_lshl_add_u64 v[62:63], v[48:49], 0, v[74:75]
	v_readlane_b32 s2, v254, 47
	v_add_co_u32_e32 v48, vcc, s11, v62
	s_nop 0
	v_or_b32_e32 v66, s2, v77
	v_mov_b32_e32 v67, v4
	v_readlane_b32 s2, v254, 26
	v_addc_co_u32_e32 v49, vcc, 0, v63, vcc
	v_lshl_add_u64 v[46:47], v[46:47], 0, v[50:51]
	v_lshlrev_b64 v[66:67], 7, v[66:67]
	v_readlane_b32 s3, v254, 27
	v_add_co_u32_e32 v50, vcc, s11, v46
	s_nop 0
	v_lshl_add_u64 v[66:67], s[2:3], 0, v[66:67]
	v_addc_co_u32_e32 v51, vcc, 0, v47, vcc
	v_lshl_add_u64 v[58:59], v[54:55], 0, s[12:13]
	v_addc_co_u32_e64 v57, vcc, 0, v55, s[6:7]
	v_lshl_add_u64 v[62:63], v[62:63], 0, s[12:13]
	v_lshl_add_u64 v[70:71], v[66:67], 0, v[74:75]
	v_lshl_add_u64 v[126:127], v[48:49], 0, s[16:17]
	global_load_dword v125, v[126:127], off offset:2304
	global_load_dwordx4 v[46:49], v[48:49], off offset:2304 nt
	s_nop 0
	v_lshl_add_u64 v[126:127], v[50:51], 0, s[16:17]
	global_load_dword v125, v[126:127], off offset:3472
	global_load_dwordx2 v[116:117], v[50:51], off offset:3472
	s_nop 0
	v_lshl_add_u64 v[126:127], v[52:53], 0, s[16:17]
	global_load_dword v125, v[126:127], off offset:64
	global_load_dwordx4 v[50:53], v[52:53], off offset:64 nt
	s_nop 0
	v_lshl_add_u64 v[126:127], v[56:57], 0, s[16:17]
	global_load_dword v125, v[126:127], off offset:2304
	global_load_dwordx4 v[54:57], v[56:57], off offset:2304 nt
	s_nop 0
	v_lshl_add_u64 v[126:127], v[58:59], 0, s[16:17]
	global_load_dword v125, v[126:127], off offset:64
	global_load_dwordx4 v[58:61], v[58:59], off offset:64 nt
	v_cmp_lt_i32_e32 vcc, v227, v226
	v_lshl_add_u64 v[126:127], v[62:63], 0, s[16:17]
	global_load_dword v125, v[126:127], off offset:64
	global_load_dwordx4 v[62:65], v[62:63], off offset:64 nt
	s_nop 0
	global_load_dwordx4 v[66:69], v[70:71], off offset:64
	s_nop 0
	global_load_dwordx4 v[70:73], v[70:71], off
	s_waitcnt vmcnt(0)
	v_lshlrev_b32_e32 v93, 16, v82
	v_and_b32_e32 v94, 0xffff0000, v82
	v_lshlrev_b32_e32 v95, 16, v83
	v_and_b32_e32 v96, 0xffff0000, v83
	v_lshl_add_u64 v[82:83], s[2:3], 0, v[74:75]
	v_cndmask_b32_e32 v74, v253, v227, vcc
	v_lshlrev_b32_e32 v118, 2, v74
	v_and_b32_e32 v74, 16, v76
	v_cmp_eq_u32_e64 s[6:7], 0, v74
	v_lshlrev_b32_e32 v74, 2, v77
	v_lshl_or_b32 v74, v119, 13, v74
	v_readlane_b32 s2, v254, 36
	v_lshlrev_b32_e32 v85, 16, v78
	v_and_b32_e32 v86, 0xffff0000, v78
	v_lshlrev_b32_e32 v87, 16, v79
	v_and_b32_e32 v88, 0xffff0000, v79
	v_lshlrev_b32_e32 v89, 16, v80
	v_and_b32_e32 v90, 0xffff0000, v80
	v_lshlrev_b32_e32 v91, 16, v81
	v_and_b32_e32 v92, 0xffff0000, v81
	v_lshlrev_b32_e32 v97, 16, v100
	v_and_b32_e32 v98, 0xffff0000, v100
	v_lshlrev_b32_e32 v99, 16, v101
	v_and_b32_e32 v100, 0xffff0000, v101
	v_lshlrev_b32_e32 v101, 16, v104
	v_and_b32_e32 v102, 0xffff0000, v104
	v_lshlrev_b32_e32 v103, 16, v105
	v_and_b32_e32 v104, 0xffff0000, v105
	v_lshlrev_b32_e32 v105, 16, v108
	v_and_b32_e32 v106, 0xffff0000, v108
	v_lshlrev_b32_e32 v107, 16, v109
	v_and_b32_e32 v108, 0xffff0000, v109
	v_add_u32_e32 v119, s2, v74
	v_readlane_b32 s10, v254, 4
	v_lshlrev_b32_e32 v109, 16, v112
	v_and_b32_e32 v110, 0xffff0000, v112
	v_lshlrev_b32_e32 v111, 16, v113
	v_and_b32_e32 v112, 0xffff0000, v113
	v_lshlrev_b32_e32 v113, 16, v116
	v_and_b32_e32 v114, 0xffff0000, v116
	v_lshlrev_b32_e32 v115, 16, v117
	v_and_b32_e32 v116, 0xffff0000, v117
	v_or_b32_e32 v117, s14, v77
	s_branch .LBB0_1085
